# v119 + a shorter copy of each parity body for key tiles off the causal band (no band flags, per-step band tests or mask blocks); the tile head selects the copy
# speedup vs baseline: 1.0020x; 1.0020x over previous
; #define ATT_LAS __attribute__((address_space(3)))
; #define ATT_STAGE(t, buf) do { _Pragma("unroll") for (int i_ = 0; i_ < 2; ++i_) { \
;         glds16(Kt + (size_t)(t) * 131072, ksrc[i_], (unsigned)__builtin_amdgcn_readfirstlane(ldsb + KBUF + (buf) * 16384 + (w * 2 + i_) * 1024)); \
;         glds16(Vt + (size_t)(t) * 131072, vsrc[i_], (unsigned)__builtin_amdgcn_readfirstlane(ldsb + VBUF + (buf) * 16384 + (w * 2 + i_) * 1024)); } } while (0)
; __device__ __forceinline__ void attn_unit(ATT_LAS unsigned char* lds, const bf16_t* Qg, const bf16_t* Kg, const bf16_t* Vg, bf16_t* Og, int b, int head, int qb, float lam, const float* subg) {
;     ...
;         if (t + 1 < NT) ATT_STAGE(t + 1, buf ^ 1);
;         const int kvrel = 64 * t - q0 - 32 * wq;
;         if (kvrel <= 31) {
;             const ATT_LAS unsigned char* kb = lds + KBUF + buf * 16384;
;             const ATT_LAS unsigned char* vb = lds + VBUF + buf * 16384;
;             tile_body(kvrel + 63 > 0, kb, vb, qbase, kaddr, vaddr, O1, O2, m1, m2, l1, l2, kvrel, r, h, wsf);
.Ltile_p0:
	s_cmp_gt_i32 s80, 31
	s_cbranch_scc1 .Ldma_skip
	s_mov_b32 s81, 0x0
	s_cmpk_gt_i32 s80, 0xffc1
	s_cbranch_scc0 .Lfast_p0

; #define ATT_LAS __attribute__((address_space(3)))
; #define ATT_STAGE(t, buf) do { _Pragma("unroll") for (int i_ = 0; i_ < 2; ++i_) { \
;         glds16(Kt + (size_t)(t) * 131072, ksrc[i_], (unsigned)__builtin_amdgcn_readfirstlane(ldsb + KBUF + (buf) * 16384 + (w * 2 + i_) * 1024)); \
;         glds16(Vt + (size_t)(t) * 131072, vsrc[i_], (unsigned)__builtin_amdgcn_readfirstlane(ldsb + VBUF + (buf) * 16384 + (w * 2 + i_) * 1024)); } } while (0)
; __device__ __forceinline__ void attn_unit(ATT_LAS unsigned char* lds, const bf16_t* Qg, const bf16_t* Kg, const bf16_t* Vg, bf16_t* Og, int b, int head, int qb, float lam, const float* subg) {
;     ...
;         if (t + 1 < NT) ATT_STAGE(t + 1, buf ^ 1);
;         const int kvrel = 64 * t - q0 - 32 * wq;
;         if (kvrel <= 31) {
;             const ATT_LAS unsigned char* kb = lds + KBUF + buf * 16384;
;             const ATT_LAS unsigned char* vb = lds + VBUF + buf * 16384;
;             tile_body(kvrel + 63 > 0, kb, vb, qbase, kaddr, vaddr, O1, O2, m1, m2, l1, l2, kvrel, r, h, wsf);
.Ltile_p1:
	s_cmp_gt_i32 s80, 31
	s_cbranch_scc1 .Ldma_skip
	s_mov_b32 s81, 0x4000
	s_cmpk_gt_i32 s80, 0xffc1
	s_cbranch_scc0 .Lfast_p1

; #define ATT_LAS __attribute__((address_space(3)))
; __device__ __forceinline__ int sub1(int a) { int v = a ^ 128; asm volatile("" : "+v"(v)); return v; }
; #define ATT_MFMA(a, b, c) __builtin_amdgcn_mfma_f32_32x32x16_bf16((a), (b), (c), 0, 0, 0)
; template <bool C1> __device__ __forceinline__ void qk_issue(f32x16& s0, const ATT_LAS unsigned char* kb, const ATT_LAS unsigned char* qb_, const int (&kaddr)[4]) {
; #pragma unroll
;     for (int i = 0; i < 16; ++i) s0[i] = 0.f;
; #pragma unroll
;     for (int ds = 0; ds < 4; ++ds) {
;         const int ad = C1 ? sub1(kaddr[ds]) : kaddr[ds];
;         const bf16x8 a0 = *(const ATT_LAS bf16x8*)(kb + ad);
;         const bf16x8 qv = *(const ATT_LAS bf16x8*)(qb_ + ad);
;         s0 = ATT_MFMA(a0, qv, s0);
;     }
; }
; __device__ __forceinline__ void tile_body(bool MASK, const ATT_LAS unsigned char* kb, const ATT_LAS unsigned char* vb, const ATT_LAS unsigned char* qbase, const int (&kaddr)[4], const int (&vaddr)[2], ...
;     ...
;     qk_issue<false>(Sa, kb, qbase, kaddr);
;     apply_mask(MASK, Sa, kvrel, r, h); ls = l1;
.Lfast_p0:
	ds_read_b128 v[2:5], v203
	ds_read_b128 v[6:9], v217
	ds_read_b128 v[10:13], v204
	ds_read_b128 v[146:149], v219
	ds_read_b128 v[150:153], v205
	ds_read_b128 v[154:157], v221
	ds_read_b128 v[158:161], v206
	ds_read_b128 v[162:165], v223
	s_waitcnt lgkmcnt(4)
	v_mfma_f32_32x32x16_bf16 v[170:185], v[2:5], v[6:9], 0
	v_mfma_f32_32x32x16_bf16 v[170:185], v[10:13], v[146:149], v[170:185]
	s_waitcnt lgkmcnt(0)
	v_mfma_f32_32x32x16_bf16 v[170:185], v[150:153], v[154:157], v[170:185]
	v_mfma_f32_32x32x16_bf16 v[170:185], v[158:161], v[162:165], v[170:185]

; #define ATT_LAS __attribute__((address_space(3)))
; __device__ __forceinline__ unsigned cvtpk(float lo, float hi) { unsigned r; asm volatile("v_cvt_pk_bf16_f32 %0, %1, %2" : "=v"(r) : "v"(lo), "v"(hi)); return r; }
; template <bool HAS_PV, bool HAS_QK, bool C1> ...
;     s16x4 vlo[2], vhi[2]; bf16x8 ka, qa;
;     if (HAS_PV) {
; #pragma unroll
;         for (int u = 0; u < 2; ++u) { vlo[u] = vtr(vb + vaddr[0] + u * 512); vhi[u] = vtr(vb + vaddr[1] + u * 512); } }
;     if (HAS_QK) { const int ad = C1 ? sub1(kaddr[0]) : kaddr[0]; ka = *(const ATT_LAS bf16x8*)(kb + ad); qa = *(const ATT_LAS bf16x8*)(qb_ + ad);
; #pragma unroll
;         for (int i = 0; i < 16; ++i) Snext[i] = 0.f; }
;     float sa = 0.f, sb = 0.f;
; #pragma unroll
;     for (int g = 0; g < 4; ++g) {
;         s16x4 nlo[2], nhi[2]; bf16x8 nk, nq;
;         if (g < 3) {
;             if (HAS_PV) {
; #pragma unroll
;                 for (int u = 0; u < 2; ++u) { const int off = (2 * ((g + 1) & 1) + u) * 512 + ((g + 1) >> 1) * 4096; nlo[u] = vtr(vb + vaddr[0] + off); nhi[u] = vtr(vb + vaddr[1] + off); } }
;             if (HAS_QK) { const int ad = C1 ? sub1(kaddr[g + 1]) : kaddr[g + 1]; nk = *(const ATT_LAS bf16x8*)(kb + ad); nq = *(const ATT_LAS bf16x8*)(qb_ + ad); }
;         }
;         if (HAS_PV) { const bf16x8 pa = __builtin_bit_cast(bf16x8, pkin[g >> 1]);
; #pragma unroll
;             for (int u = 0; u < 2; ++u) { const bf16x8 vf = __builtin_shufflevector(vlo[u], vhi[u], 0, 1, 2, 3, 4, 5, 6, 7); Opv[2 * (g & 1) + u] = ATT_MFMA(pa, vf, Opv[2 * (g & 1) + u]); } }
;         if (HAS_QK) Snext = ATT_MFMA(ka, qa, Snext);
; #pragma unroll
;         for (int e = 4 * g; e < 4 * g + 4; e += 2) { Scur[e] = __builtin_amdgcn_exp2f(Scur[e] - m); Scur[e + 1] = __builtin_amdgcn_exp2f(Scur[e + 1] - m); sa += Scur[e]; sb += Scur[e + 1]; }
;         if (g & 1) pkout[g >> 1] = (u32x4){cvtpk(Scur[4 * g - 4], Scur[4 * g - 3]), cvtpk(Scur[4 * g - 2], Scur[4 * g - 1]), cvtpk(Scur[4 * g], Scur[4 * g + 1]), cvtpk(Scur[4 * g + 2], Scur[4 * g + 3])};
;         if (g < 3) {
;             if (HAS_PV) {
; #pragma unroll
;                 for (int u = 0; u < 2; ++u) { vlo[u] = nlo[u]; vhi[u] = nhi[u]; } }
;             if (HAS_QK) { ka = nk; qa = nq; }
;         }
;         __builtin_amdgcn_sched_barrier(0);
;     }
;     l += sa + sb;
;     return sa + sb;
; }
.Lns_296_p0f:
	ds_read_b128 v[2:5], v209
	ds_read_b128 v[6:9], v244
	s_nop 1
	ds_read_b128 v[10:13], v210
	ds_read_b128 v[146:149], v245
	v_exp_f32_e32 v15, v170
	v_exp_f32_e32 v14, v171
	v_exp_f32_e32 v155, v172
	v_exp_f32_e32 v154, v173
	s_waitcnt lgkmcnt(2)
	v_mfma_f32_32x32x16_bf16 v[158:173], v[2:5], v[6:9], 0
	s_waitcnt lgkmcnt(0)
	v_mfma_f32_32x32x16_bf16 v[158:173], v[10:13], v[146:149], v[158:173]
	ds_read_b128 v[6:9], v211
	ds_read_b128 v[150:153], v246
	v_exp_f32_e32 v157, v174
	v_exp_f32_e32 v156, v175
	v_exp_f32_e32 v175, v176
	v_exp_f32_e32 v174, v177
	v_cvt_pk_bf16_f32 v2, v15, v14
	v_cvt_pk_bf16_f32 v3, v155, v154
	v_cvt_pk_bf16_f32 v4, v157, v156
	v_cvt_pk_bf16_f32 v5, v175, v174
	s_waitcnt lgkmcnt(0)
	v_mfma_f32_32x32x16_bf16 v[158:173], v[6:9], v[150:153], v[158:173]
	ds_read_b128 v[10:13], v212
	ds_read_b128 v[146:149], v247
	v_exp_f32_e32 v177, v178
	v_exp_f32_e32 v176, v179
	v_exp_f32_e32 v179, v180
	v_exp_f32_e32 v178, v181
	s_waitcnt lgkmcnt(0)
	v_mfma_f32_32x32x16_bf16 v[158:173], v[10:13], v[146:149], v[158:173]
	v_exp_f32_e32 v7, v182
	v_add_f32_e32 v14, v154, v14
	v_add_f32_e32 v15, v155, v15
	v_exp_f32_e32 v6, v183
	v_exp_f32_e32 v9, v184
	v_add_f32_e32 v14, v156, v14
	v_add_f32_e32 v15, v157, v15
	v_exp_f32_e32 v8, v185
	v_add_f32_e32 v14, v174, v14
	v_add_f32_e32 v15, v175, v15
	v_cvt_pk_bf16_f32 v10, v177, v176
	v_cvt_pk_bf16_f32 v11, v179, v178
	v_cvt_pk_bf16_f32 v12, v7, v6
	v_cvt_pk_bf16_f32 v13, v9, v8
	v_add_f32_e32 v14, v176, v14
	v_add_f32_e32 v15, v177, v15
	v_add_f32_e32 v14, v178, v14
	v_add_f32_e32 v15, v179, v15
	v_add_f32_e32 v6, v6, v14
	v_add_f32_e32 v7, v7, v15
	v_add_f32_e32 v6, v8, v6
	v_add_f32_e32 v7, v9, v7
	v_add_f32_e32 v6, v6, v7
	v_cmp_nge_f32_e32 vcc, s58, v6
	s_cbranch_vccnz .Ltramp_slow_1
.Lns_305_p0f:
	v_add_f32_e32 v180, v225, v6
.Lns_311_p0f:
	s_add_i32 m0, s50, 0x4000
	s_cmp_ge_u32 s79, s76
	s_cbranch_scc1 .Ldma_ns2_p0f
	global_load_lds_dwordx4 v200, s[92:93]

; template <bool HAS_PV, bool HAS_QK, bool C1> ...
;     ...
;     l += sa + sb;
;     return sa + sb;
.Lns_320_p0f:
	v_add_f32_e32 v181, v224, v10
.Lns_326_p0f:
	s_add_i32 m0, s50, 0xc000
	s_cmp_ge_u32 s79, s76
	s_cbranch_scc1 .Ldma_ns3_p0f
	global_load_lds_dwordx4 v201, s[94:95]

; #define ATT_LAS __attribute__((address_space(3)))
; __device__ __forceinline__ int sub1(int a) { int v = a ^ 128; asm volatile("" : "+v"(v)); return v; }
; #define ATT_MFMA(a, b, c) __builtin_amdgcn_mfma_f32_32x32x16_bf16((a), (b), (c), 0, 0, 0)
; template <bool C1> __device__ __forceinline__ void qk_issue(f32x16& s0, const ATT_LAS unsigned char* kb, const ATT_LAS unsigned char* qb_, const int (&kaddr)[4]) {
; #pragma unroll
;     for (int i = 0; i < 16; ++i) s0[i] = 0.f;
; #pragma unroll
;     for (int ds = 0; ds < 4; ++ds) {
;         const int ad = C1 ? sub1(kaddr[ds]) : kaddr[ds];
;         const bf16x8 a0 = *(const ATT_LAS bf16x8*)(kb + ad);
;         const bf16x8 qv = *(const ATT_LAS bf16x8*)(qb_ + ad);
;         s0 = ATT_MFMA(a0, qv, s0);
;     }
; }
; __device__ __forceinline__ void tile_body(bool MASK, const ATT_LAS unsigned char* kb, const ATT_LAS unsigned char* vb, const ATT_LAS unsigned char* qbase, const int (&kaddr)[4], const int (&vaddr)[2], ...
;     ...
;     qk_issue<false>(Sa, kb, qbase, kaddr);
;     apply_mask(MASK, Sa, kvrel, r, h); ls = l1;
.Lfast_p1:
	ds_read_b128 v[2:5], v203 offset:16384
	ds_read_b128 v[6:9], v217
	ds_read_b128 v[10:13], v204 offset:16384
	ds_read_b128 v[146:149], v219
	ds_read_b128 v[150:153], v205 offset:16384
	ds_read_b128 v[154:157], v221
	ds_read_b128 v[158:161], v206 offset:16384
	ds_read_b128 v[162:165], v223
	s_waitcnt lgkmcnt(4)
	v_mfma_f32_32x32x16_bf16 v[170:185], v[2:5], v[6:9], 0
	v_mfma_f32_32x32x16_bf16 v[170:185], v[10:13], v[146:149], v[170:185]
	s_waitcnt lgkmcnt(0)
	v_mfma_f32_32x32x16_bf16 v[170:185], v[150:153], v[154:157], v[170:185]
	v_mfma_f32_32x32x16_bf16 v[170:185], v[158:161], v[162:165], v[170:185]

; #define ATT_LAS __attribute__((address_space(3)))
; __device__ __forceinline__ unsigned cvtpk(float lo, float hi) { unsigned r; asm volatile("v_cvt_pk_bf16_f32 %0, %1, %2" : "=v"(r) : "v"(lo), "v"(hi)); return r; }
; template <bool HAS_PV, bool HAS_QK, bool C1> ...
;     s16x4 vlo[2], vhi[2]; bf16x8 ka, qa;
;     if (HAS_PV) {
; #pragma unroll
;         for (int u = 0; u < 2; ++u) { vlo[u] = vtr(vb + vaddr[0] + u * 512); vhi[u] = vtr(vb + vaddr[1] + u * 512); } }
;     if (HAS_QK) { const int ad = C1 ? sub1(kaddr[0]) : kaddr[0]; ka = *(const ATT_LAS bf16x8*)(kb + ad); qa = *(const ATT_LAS bf16x8*)(qb_ + ad);
; #pragma unroll
;         for (int i = 0; i < 16; ++i) Snext[i] = 0.f; }
;     float sa = 0.f, sb = 0.f;
; #pragma unroll
;     for (int g = 0; g < 4; ++g) {
;         s16x4 nlo[2], nhi[2]; bf16x8 nk, nq;
;         if (g < 3) {
;             if (HAS_PV) {
; #pragma unroll
;                 for (int u = 0; u < 2; ++u) { const int off = (2 * ((g + 1) & 1) + u) * 512 + ((g + 1) >> 1) * 4096; nlo[u] = vtr(vb + vaddr[0] + off); nhi[u] = vtr(vb + vaddr[1] + off); } }
;             if (HAS_QK) { const int ad = C1 ? sub1(kaddr[g + 1]) : kaddr[g + 1]; nk = *(const ATT_LAS bf16x8*)(kb + ad); nq = *(const ATT_LAS bf16x8*)(qb_ + ad); }
;         }
;         if (HAS_PV) { const bf16x8 pa = __builtin_bit_cast(bf16x8, pkin[g >> 1]);
; #pragma unroll
;             for (int u = 0; u < 2; ++u) { const bf16x8 vf = __builtin_shufflevector(vlo[u], vhi[u], 0, 1, 2, 3, 4, 5, 6, 7); Opv[2 * (g & 1) + u] = ATT_MFMA(pa, vf, Opv[2 * (g & 1) + u]); } }
;         if (HAS_QK) Snext = ATT_MFMA(ka, qa, Snext);
; #pragma unroll
;         for (int e = 4 * g; e < 4 * g + 4; e += 2) { Scur[e] = __builtin_amdgcn_exp2f(Scur[e] - m); Scur[e + 1] = __builtin_amdgcn_exp2f(Scur[e + 1] - m); sa += Scur[e]; sb += Scur[e + 1]; }
;         if (g & 1) pkout[g >> 1] = (u32x4){cvtpk(Scur[4 * g - 4], Scur[4 * g - 3]), cvtpk(Scur[4 * g - 2], Scur[4 * g - 1]), cvtpk(Scur[4 * g], Scur[4 * g + 1]), cvtpk(Scur[4 * g + 2], Scur[4 * g + 3])};
;         if (g < 3) {
;             if (HAS_PV) {
; #pragma unroll
;                 for (int u = 0; u < 2; ++u) { vlo[u] = nlo[u]; vhi[u] = nhi[u]; } }
;             if (HAS_QK) { ka = nk; qa = nq; }
;         }
;         __builtin_amdgcn_sched_barrier(0);
;     }
;     l += sa + sb;
;     return sa + sb;
; }
.Lns_296_p1f:
	ds_read_b128 v[2:5], v209 offset:16384
	ds_read_b128 v[6:9], v244
	s_nop 1
	ds_read_b128 v[10:13], v210 offset:16384
	ds_read_b128 v[146:149], v245
	v_exp_f32_e32 v15, v170
	v_exp_f32_e32 v14, v171
	v_exp_f32_e32 v155, v172
	v_exp_f32_e32 v154, v173
	s_waitcnt lgkmcnt(2)
	v_mfma_f32_32x32x16_bf16 v[158:173], v[2:5], v[6:9], 0
	s_waitcnt lgkmcnt(0)
	v_mfma_f32_32x32x16_bf16 v[158:173], v[10:13], v[146:149], v[158:173]
	ds_read_b128 v[6:9], v211 offset:16384
	ds_read_b128 v[150:153], v246
	v_exp_f32_e32 v157, v174
	v_exp_f32_e32 v156, v175
	v_exp_f32_e32 v175, v176
	v_exp_f32_e32 v174, v177
	v_cvt_pk_bf16_f32 v2, v15, v14
	v_cvt_pk_bf16_f32 v3, v155, v154
	v_cvt_pk_bf16_f32 v4, v157, v156
	v_cvt_pk_bf16_f32 v5, v175, v174
	s_waitcnt lgkmcnt(0)
	v_mfma_f32_32x32x16_bf16 v[158:173], v[6:9], v[150:153], v[158:173]
	ds_read_b128 v[10:13], v212 offset:16384
	ds_read_b128 v[146:149], v247
	v_exp_f32_e32 v177, v178
	v_exp_f32_e32 v176, v179
	v_exp_f32_e32 v179, v180
	v_exp_f32_e32 v178, v181
	s_waitcnt lgkmcnt(0)
	v_mfma_f32_32x32x16_bf16 v[158:173], v[10:13], v[146:149], v[158:173]
	v_exp_f32_e32 v7, v182
	v_add_f32_e32 v14, v154, v14
	v_add_f32_e32 v15, v155, v15
	v_exp_f32_e32 v6, v183
	v_exp_f32_e32 v9, v184
	v_add_f32_e32 v14, v156, v14
	v_add_f32_e32 v15, v157, v15
	v_exp_f32_e32 v8, v185
	v_add_f32_e32 v14, v174, v14
	v_add_f32_e32 v15, v175, v15
	v_cvt_pk_bf16_f32 v10, v177, v176
	v_cvt_pk_bf16_f32 v11, v179, v178
	v_cvt_pk_bf16_f32 v12, v7, v6
	v_cvt_pk_bf16_f32 v13, v9, v8
	v_add_f32_e32 v14, v176, v14
	v_add_f32_e32 v15, v177, v15
	v_add_f32_e32 v14, v178, v14
	v_add_f32_e32 v15, v179, v15
	v_add_f32_e32 v6, v6, v14
	v_add_f32_e32 v7, v7, v15
	v_add_f32_e32 v6, v8, v6
	v_add_f32_e32 v7, v9, v7
	v_add_f32_e32 v6, v6, v7
	v_cmp_nge_f32_e32 vcc, s58, v6
	s_cbranch_vccnz .Ltramp_slow_1
.Lns_305_p1f:
	v_add_f32_e32 v180, v225, v6
.Lns_311_p1f:
	s_mov_b32 m0, s50
	s_cmp_ge_u32 s79, s76
	s_cbranch_scc1 .Ldma_ns2_p1f
	global_load_lds_dwordx4 v200, s[92:93]

; template <bool HAS_PV, bool HAS_QK, bool C1> ...
;     ...
;     l += sa + sb;
;     return sa + sb;
.Lns_320_p1f:
	v_add_f32_e32 v181, v224, v10
.Lns_326_p1f:
	s_add_i32 m0, s50, 0x8000
	s_cmp_ge_u32 s79, s76
	s_cbranch_scc1 .Ldma_ns3_p1f
	global_load_lds_dwordx4 v201, s[94:95]

; template <bool HAS_PV, bool HAS_QK, bool C1> ...
;     s16x4 vlo[2], vhi[2]; bf16x8 ka, qa;
;     if (HAS_PV) {
; #pragma unroll
;         for (int u = 0; u < 2; ++u) { vlo[u] = vtr(vb + vaddr[0] + u * 512); vhi[u] = vtr(vb + vaddr[1] + u * 512); } }
;     if (HAS_QK) { const int ad = C1 ? sub1(kaddr[0]) : kaddr[0]; ka = *(const ATT_LAS bf16x8*)(kb + ad); qa = *(const ATT_LAS bf16x8*)(qb_ + ad);
; #pragma unroll
;         for (int i = 0; i < 16; ++i) Snext[i] = 0.f; }
;     float sa = 0.f, sb = 0.f;
; #pragma unroll
;     for (int g = 0; g < 4; ++g) {
;         s16x4 nlo[2], nhi[2]; bf16x8 nk, nq;
;         if (g < 3) {
;             if (HAS_PV) {
; #pragma unroll
;                 for (int u = 0; u < 2; ++u) { const int off = (2 * ((g + 1) & 1) + u) * 512 + ((g + 1) >> 1) * 4096; nlo[u] = vtr(vb + vaddr[0] + off); nhi[u] = vtr(vb + vaddr[1] + off); } }
;             if (HAS_QK) { const int ad = C1 ? sub1(kaddr[g + 1]) : kaddr[g + 1]; nk = *(const ATT_LAS bf16x8*)(kb + ad); nq = *(const ATT_LAS bf16x8*)(qb_ + ad); }
;         }
;         if (HAS_PV) { const bf16x8 pa = __builtin_bit_cast(bf16x8, pkin[g >> 1]);
; #pragma unroll
;             for (int u = 0; u < 2; ++u) { const bf16x8 vf = __builtin_shufflevector(vlo[u], vhi[u], 0, 1, 2, 3, 4, 5, 6, 7); Opv[2 * (g & 1) + u] = ATT_MFMA(pa, vf, Opv[2 * (g & 1) + u]); } }
;         if (HAS_QK) Snext = ATT_MFMA(ka, qa, Snext);
; #pragma unroll
;         for (int e = 4 * g; e < 4 * g + 4; e += 2) { Scur[e] = __builtin_amdgcn_exp2f(Scur[e] - m); Scur[e + 1] = __builtin_amdgcn_exp2f(Scur[e + 1] - m); sa += Scur[e]; sb += Scur[e + 1]; }
;         if (g & 1) pkout[g >> 1] = (u32x4){cvtpk(Scur[4 * g - 4], Scur[4 * g - 3]), cvtpk(Scur[4 * g - 2], Scur[4 * g - 1]), cvtpk(Scur[4 * g], Scur[4 * g + 1]), cvtpk(Scur[4 * g + 2], Scur[4 * g + 3])};
;         if (g < 3) {
;             if (HAS_PV) {
; #pragma unroll
;                 for (int u = 0; u < 2; ++u) { vlo[u] = nlo[u]; vhi[u] = nhi[u]; } }
;             if (HAS_QK) { ka = nk; qa = nq; }
;         }
;         __builtin_amdgcn_sched_barrier(0);
;     }
;     l += sa + sb;
;     return sa + sb;
; }
; __device__ __forceinline__ void pv_issue(f32x16 (&O)[4], const u32x4 (&pk)[2], const ATT_LAS unsigned char* vb, const int (&vaddr)[2]) {
; #pragma unroll
;     for (int s_ = 0; s_ < 2; ++s_) { const bf16x8 pa = __builtin_bit_cast(bf16x8, pk[s_]);
; #pragma unroll
.Lns_335_p1f:
	v_add_f32_e32 v225, v180, v6
.Lns_341_p1f:
	ds_read_b64_tr_b16 v[8:9], v213 offset:59392
	ds_read_b64_tr_b16 v[6:7], v207 offset:57344
	ds_read_b64_tr_b16 v[146:147], v207 offset:57856
	ds_read_b64_tr_b16 v[150:151], v207 offset:58368
	ds_read_b64_tr_b16 v[154:155], v207 offset:58880
	ds_read_b64_tr_b16 v[148:149], v213 offset:59904
	ds_read_b64_tr_b16 v[152:153], v213 offset:60416
	ds_read_b64_tr_b16 v[156:157], v213 offset:60928
	s_waitcnt lgkmcnt(1)
	v_mfma_f32_32x32x16_bf16 v[34:49], v[2:5], v[6:9], v[34:49]
	v_exp_f32_e32 v15, v162
	v_exp_f32_e32 v14, v163
	v_exp_f32_e32 v163, v164
	v_mfma_f32_32x32x16_bf16 v[50:65], v[2:5], v[146:149], v[50:65]
	v_exp_f32_e32 v162, v165
	v_mfma_f32_32x32x16_bf16 v[66:81], v[2:5], v[150:153], v[66:81]
	ds_read_b64_tr_b16 v[146:147], v207 offset:61440
	ds_read_b64_tr_b16 v[148:149], v213 offset:63488
	ds_read_b64_tr_b16 v[160:161], v213 offset:64000
	ds_read_b64_tr_b16 v[158:159], v207 offset:61952
	v_exp_f32_e32 v165, v166
	v_exp_f32_e32 v164, v167
	v_exp_f32_e32 v167, v168
	s_waitcnt lgkmcnt(2)
	v_mfma_f32_32x32x16_bf16 v[82:97], v[2:5], v[154:157], v[82:97]
	v_exp_f32_e32 v166, v169
	v_cvt_pk_bf16_f32 v6, v15, v14
	v_cvt_pk_bf16_f32 v7, v163, v162
	v_cvt_pk_bf16_f32 v8, v165, v164
	v_cvt_pk_bf16_f32 v9, v167, v166
	v_mfma_f32_32x32x16_bf16 v[34:49], v[10:13], v[146:149], v[34:49]
	ds_read_b64_tr_b16 v[2:3], v207 offset:62464
	ds_read_b64_tr_b16 v[4:5], v213 offset:64512
	ds_read_b64_tr_b16 v[152:153], v213 offset:65024
	ds_read_b64_tr_b16 v[150:151], v207 offset:62976
	v_exp_f32_e32 v147, v170
	v_exp_f32_e32 v146, v171
	v_exp_f32_e32 v149, v172
	s_waitcnt lgkmcnt(0)
	v_mfma_f32_32x32x16_bf16 v[50:65], v[10:13], v[158:161], v[50:65]
	v_exp_f32_e32 v148, v173
	v_mfma_f32_32x32x16_bf16 v[66:81], v[10:13], v[2:5], v[66:81]
	v_exp_f32_e32 v155, v174
	v_exp_f32_e32 v154, v175
	v_exp_f32_e32 v157, v176
	v_mfma_f32_32x32x16_bf16 v[82:97], v[10:13], v[150:153], v[82:97]
	v_add_f32_e64 v10, v162, v14
	v_add_f32_e64 v11, v163, v15
	v_exp_f32_e32 v156, v177
	v_add_f32_e32 v10, v164, v10
	v_add_f32_e32 v11, v165, v11
	v_cvt_pk_bf16_f32 v2, v147, v146
	v_cvt_pk_bf16_f32 v3, v149, v148
	v_cvt_pk_bf16_f32 v4, v155, v154
	v_cvt_pk_bf16_f32 v5, v157, v156
	v_add_f32_e32 v10, v166, v10
	v_add_f32_e32 v11, v167, v11
	v_add_f32_e32 v10, v146, v10
	v_add_f32_e32 v11, v147, v11
	v_add_f32_e32 v10, v148, v10
	v_add_f32_e32 v11, v149, v11
	v_add_f32_e32 v10, v154, v10
	v_add_f32_e32 v11, v155, v11
	v_add_f32_e32 v10, v156, v10
	v_add_f32_e32 v11, v157, v11
	v_add_f32_e32 v10, v10, v11
	v_cmp_nge_f32_e32 vcc, s58, v10
	s_cbranch_vccnz .Ltramp_slow_4
	v_add_f32_e32 v224, v181, v10
	ds_read_b64_tr_b16 v[12:13], v213 offset:59392
	ds_read_b64_tr_b16 v[10:11], v207 offset:57344
	ds_read_b64_tr_b16 v[146:147], v207 offset:57856
	ds_read_b64_tr_b16 v[150:151], v207 offset:58368
	ds_read_b64_tr_b16 v[154:155], v207 offset:58880
	ds_read_b64_tr_b16 v[148:149], v213 offset:59904
	ds_read_b64_tr_b16 v[152:153], v213 offset:60416
	ds_read_b64_tr_b16 v[156:157], v213 offset:60928
	ds_read_b64_tr_b16 v[160:161], v213 offset:63488
	ds_read_b64_tr_b16 v[158:159], v207 offset:61440
	ds_read_b64_tr_b16 v[162:163], v207 offset:61952
	ds_read_b64_tr_b16 v[166:167], v207 offset:62464
	ds_read_b64_tr_b16 v[170:171], v207 offset:62976
	ds_read_b64_tr_b16 v[164:165], v213 offset:64000
	ds_read_b64_tr_b16 v[168:169], v213 offset:64512
	s_waitcnt lgkmcnt(7)
	v_mfma_f32_32x32x16_bf16 v[130:145], v[6:9], v[10:13], v[130:145]
	v_mfma_f32_32x32x16_bf16 v[114:129], v[6:9], v[146:149], v[114:129]
	v_mfma_f32_32x32x16_bf16 v[98:113], v[6:9], v[150:153], v[98:113]
	v_mfma_f32_32x32x16_bf16 v[18:33], v[6:9], v[154:157], v[18:33]
	ds_read_b64_tr_b16 v[172:173], v213 offset:65024
	s_waitcnt lgkmcnt(0)
	v_mfma_f32_32x32x16_bf16 v[130:145], v[2:5], v[158:161], v[130:145]
	v_mfma_f32_32x32x16_bf16 v[114:129], v[2:5], v[162:165], v[114:129]
	v_mfma_f32_32x32x16_bf16 v[98:113], v[2:5], v[166:169], v[98:113]
	v_mfma_f32_32x32x16_bf16 v[18:33], v[2:5], v[170:173], v[18:33]
	s_add_i32 s80, s80, 64
	s_add_u32 s94, s94, 0x20000
	s_addc_u32 s95, s95, 0
	s_waitcnt vmcnt(0)
	s_add_u32 s92, s92, 0x20000
	s_addc_u32 s93, s93, 0
	s_cmp_eq_u32 s76, s79
	v_subrev_u32_e32 v214, 64, v214
	s_barrier
	s_cbranch_scc0 .Lhead_p0
	s_branch .LBB0_352
.Ldisp_check_p1f:
	v_or_b32_e32 v252, v0, v215
	v_cmp_eq_u32_e32 vcc, 0, v252
	s_cmp_eq_u64 vcc, exec
	s_cbranch_scc0 .Ltramp_orig
	s_mov_b32 s101, 1
	s_branch .Lns_296_p1f
.Ltramp_slow_1:
	s_mov_b64 s[36:37], 0
	s_mov_b64 s[4:5], exec
	s_branch .Lfix_slow_1
